# cache policy: nt on the generic conversion loop's bf16 weight stores (keep x / operands resident), on top of v71
# baseline (speedup 1.0000x reference)
.LBB0_90:
	s_mov_b64 s[22:23], 0
	global_store_dwordx4 v[6:7], v[2:5], off nt

.LBB0_108:
	s_ashr_i32 s24, s47, 31
	s_lshr_b32 s24, s24, 26
	s_add_i32 s24, s47, s24
	s_andn2_b32 s24, s24, 63
	v_readlane_b32 s52, v240, 2
	s_sub_i32 s25, s47, s24
	s_mul_i32 s26, s46, 0xac00000
	v_readlane_b32 s58, v240, 8
	v_readlane_b32 s59, v240, 9
	s_add_u32 s48, s58, s26
	s_addc_u32 s49, s59, 0
	v_readlane_b32 s53, v240, 3
	s_add_u32 s52, s84, s28
	s_addc_u32 s53, s85, s29
	s_lshl_b32 s26, s25, 6
	s_ashr_i32 s27, s26, 31
	v_or_b32_e32 v30, s24, v66
	s_lshl_b64 s[28:29], s[26:27], 2
	s_add_u32 s28, s48, s28
	v_or_b32_e32 v6, 1, v30
	s_addc_u32 s29, s49, s29
	v_ashrrev_i32_e32 v31, 31, v30
	v_ashrrev_i32_e32 v7, 31, v6
	v_or_b32_e32 v10, 2, v30
	v_or_b32_e32 v14, 3, v30
	v_or_b32_e32 v18, 4, v30
	v_or_b32_e32 v22, 5, v30
	v_or_b32_e32 v26, 6, v30
	v_lshl_add_u64 v[32:33], s[28:29], 0, v[70:71]
	v_lshlrev_b64 v[2:3], 14, v[30:31]
	v_lshlrev_b64 v[6:7], 14, v[6:7]
	v_ashrrev_i32_e32 v11, 31, v10
	v_ashrrev_i32_e32 v15, 31, v14
	v_ashrrev_i32_e32 v19, 31, v18
	v_ashrrev_i32_e32 v23, 31, v22
	v_ashrrev_i32_e32 v27, 31, v26
	v_lshl_add_u64 v[34:35], v[32:33], 0, v[2:3]
	v_lshl_add_u64 v[38:39], v[32:33], 0, v[6:7]
	v_lshlrev_b64 v[10:11], 14, v[10:11]
	v_lshlrev_b64 v[14:15], 14, v[14:15]
	v_lshlrev_b64 v[18:19], 14, v[18:19]
	v_lshlrev_b64 v[22:23], 14, v[22:23]
	v_lshlrev_b64 v[26:27], 14, v[26:27]
	v_or_b32_e32 v30, 7, v30
	global_load_dwordx4 v[2:5], v[34:35], off nt
	global_load_dwordx4 v[6:9], v[38:39], off nt
	v_lshl_add_u64 v[42:43], v[32:33], 0, v[10:11]
	v_lshl_add_u64 v[46:47], v[32:33], 0, v[14:15]
	v_lshl_add_u64 v[50:51], v[32:33], 0, v[18:19]
	v_lshl_add_u64 v[54:55], v[32:33], 0, v[22:23]
	v_lshl_add_u64 v[58:59], v[32:33], 0, v[26:27]
	v_ashrrev_i32_e32 v31, 31, v30
	global_load_dwordx4 v[10:13], v[42:43], off nt
	global_load_dwordx4 v[14:17], v[46:47], off nt
	global_load_dwordx4 v[18:21], v[50:51], off nt
	global_load_dwordx4 v[22:25], v[54:55], off nt
	global_load_dwordx4 v[26:29], v[58:59], off nt
	v_lshlrev_b64 v[30:31], 14, v[30:31]
	v_lshl_add_u64 v[62:63], v[32:33], 0, v[30:31]
	global_load_dwordx4 v[30:33], v[62:63], off nt
	s_nop 0
	global_load_dwordx4 v[34:37], v[34:35], off offset:128 nt
	s_nop 0
	global_load_dwordx4 v[38:41], v[38:39], off offset:128 nt
	s_nop 0
	global_load_dwordx4 v[42:45], v[42:43], off offset:128 nt
	s_nop 0
	global_load_dwordx4 v[46:49], v[46:47], off offset:128 nt
	s_nop 0
	global_load_dwordx4 v[50:53], v[50:51], off offset:128 nt
	s_nop 0
	global_load_dwordx4 v[54:57], v[54:55], off offset:128 nt
	s_nop 0
	global_load_dwordx4 v[58:61], v[58:59], off offset:128 nt
	s_nop 0
	global_load_dwordx4 v[62:65], v[62:63], off offset:128 nt
	s_ashr_i32 s25, s24, 31
	s_lshl_b64 s[24:25], s[24:25], 1
	v_or_b32_e32 v1, s26, v68
	s_add_u32 s24, s52, s24
	v_mov_b32_e32 v79, v71
	v_mul_lo_u32 v80, v1, s36
	s_addc_u32 s25, s53, s25
	v_ashrrev_i32_e32 v81, 31, v80
	v_lshl_add_u64 v[82:83], s[24:25], 0, v[78:79]
	v_lshl_add_u64 v[92:93], v[80:81], 1, v[82:83]
	v_add_co_u32_e32 v94, vcc, s37, v92
	v_readlane_b32 s54, v240, 4
	s_nop 0
	v_addc_co_u32_e32 v95, vcc, 0, v93, vcc
	v_add_co_u32_e32 v96, vcc, s38, v92
	v_readlane_b32 s55, v240, 5
	s_nop 0
	v_addc_co_u32_e32 v97, vcc, 0, v93, vcc
	v_readlane_b32 s56, v240, 6
	v_readlane_b32 s57, v240, 7
	s_mov_b64 s[24:25], 0
	s_waitcnt vmcnt(14)
	v_cvt_pk_bf16_f32 v80, v2, v6
	v_add_co_u32_e32 v6, vcc, s39, v92
	v_cvt_pk_bf16_f32 v84, v3, v7
	v_cvt_pk_bf16_f32 v88, v4, v8
	v_cvt_pk_bf16_f32 v2, v5, v9
	v_addc_co_u32_e32 v7, vcc, 0, v93, vcc
	s_waitcnt vmcnt(12)
	v_cvt_pk_bf16_f32 v81, v10, v14
	v_cvt_pk_bf16_f32 v3, v13, v17
	s_waitcnt vmcnt(10)
	v_cvt_pk_bf16_f32 v82, v18, v22
	s_waitcnt vmcnt(8)
	v_cvt_pk_bf16_f32 v83, v26, v30
	v_cvt_pk_bf16_f32 v4, v21, v25
	v_cvt_pk_bf16_f32 v5, v29, v33
	v_cvt_pk_bf16_f32 v85, v11, v15
	v_cvt_pk_bf16_f32 v86, v19, v23
	v_cvt_pk_bf16_f32 v87, v27, v31
	v_cvt_pk_bf16_f32 v89, v12, v16
	v_cvt_pk_bf16_f32 v90, v20, v24
	v_cvt_pk_bf16_f32 v91, v28, v32
	global_store_dwordx4 v[92:93], v[80:83], off nt
	global_store_dwordx4 v[94:95], v[84:87], off offset:1536 nt
	global_store_dwordx4 v[96:97], v[88:91], off offset:3072 nt
	global_store_dwordx4 v[6:7], v[2:5], off offset:512 nt
	v_add_co_u32_e32 v6, vcc, s40, v92
	s_waitcnt vmcnt(10)
	v_cvt_pk_bf16_f32 v2, v34, v38
	s_waitcnt vmcnt(8)
	v_cvt_pk_bf16_f32 v3, v42, v46
	s_waitcnt vmcnt(6)
	v_cvt_pk_bf16_f32 v4, v50, v54
	s_waitcnt vmcnt(4)
	v_cvt_pk_bf16_f32 v5, v58, v62
	v_addc_co_u32_e32 v7, vcc, 0, v93, vcc
	global_store_dwordx4 v[6:7], v[2:5], off nt
	v_add_co_u32_e32 v6, vcc, s41, v92
	s_nop 0
	v_cvt_pk_bf16_f32 v2, v35, v39
	v_cvt_pk_bf16_f32 v3, v43, v47
	v_cvt_pk_bf16_f32 v4, v51, v55
	v_cvt_pk_bf16_f32 v5, v59, v63
	v_addc_co_u32_e32 v7, vcc, 0, v93, vcc
	global_store_dwordx4 v[6:7], v[2:5], off offset:1536 nt
	v_add_co_u32_e32 v6, vcc, s42, v92
	s_nop 0
	v_cvt_pk_bf16_f32 v2, v36, v40
	v_cvt_pk_bf16_f32 v3, v44, v48
	v_cvt_pk_bf16_f32 v4, v52, v56
	v_cvt_pk_bf16_f32 v5, v60, v64
	v_addc_co_u32_e32 v7, vcc, 0, v93, vcc
	global_store_dwordx4 v[6:7], v[2:5], off offset:3072 nt
	v_lshl_add_u64 v[6:7], v[92:93], 0, s[4:5]
	s_nop 0
	v_cvt_pk_bf16_f32 v2, v37, v41
	v_cvt_pk_bf16_f32 v3, v45, v49
	v_cvt_pk_bf16_f32 v4, v53, v57
	v_cvt_pk_bf16_f32 v5, v61, v65

.LBB0_112:
	s_add_u32 s27, s84, s22
	s_addc_u32 s29, s85, s23
	s_cmpk_lt_i32 s28, 0xac
	s_cselect_b32 s22, 0, 0xffffd500
	s_cselect_b32 s23, 0, 0x80
	s_add_i32 s22, s22, s26
	s_lshl_b32 s22, s22, 1
	s_and_b32 s26, s26, 64
	s_and_b32 s22, s22, 0xffffff00
	s_or_b32 s23, s23, s26
	s_or_b32 s22, s23, s22
	v_or_b32_e32 v84, s22, v68
	s_lshl_b64 s[22:23], s[24:25], 1
	s_add_u32 s22, s27, s22
	s_addc_u32 s23, s29, s23
	v_mov_b32_e32 v79, v71
	v_ashrrev_i32_e32 v85, 31, v84
	v_lshl_add_u64 v[86:87], s[22:23], 0, v[78:79]
	v_lshlrev_b64 v[88:89], 13, v[84:85]
	s_waitcnt vmcnt(13)
	v_cvt_pk_bf16_f32 v80, v34, v38
	s_waitcnt vmcnt(9)
	v_cvt_pk_bf16_f32 v81, v42, v46
	s_waitcnt vmcnt(5)
	v_cvt_pk_bf16_f32 v82, v50, v54
	s_waitcnt vmcnt(1)
	v_cvt_pk_bf16_f32 v83, v58, v62
	v_lshl_add_u64 v[88:89], v[86:87], 0, v[88:89]
	v_or_b32_e32 v34, 1, v84
	global_store_dwordx4 v[88:89], v[80:83], off nt
	v_or_b32_e32 v38, 3, v84
	s_nop 0
	v_cvt_pk_bf16_f32 v80, v35, v39
	v_ashrrev_i32_e32 v35, 31, v34
	v_lshlrev_b64 v[34:35], 13, v[34:35]
	v_cvt_pk_bf16_f32 v81, v43, v47
	v_cvt_pk_bf16_f32 v82, v51, v55
	v_cvt_pk_bf16_f32 v83, v59, v63
	v_lshl_add_u64 v[34:35], v[86:87], 0, v[34:35]
	global_store_dwordx4 v[34:35], v[80:83], off nt
	v_or_b32_e32 v34, 2, v84
	v_ashrrev_i32_e32 v35, 31, v34
	v_lshlrev_b64 v[34:35], 13, v[34:35]
	v_ashrrev_i32_e32 v39, 31, v38
	v_cvt_pk_bf16_f32 v80, v36, v40
	v_cvt_pk_bf16_f32 v81, v44, v48
	v_cvt_pk_bf16_f32 v82, v52, v56
	v_cvt_pk_bf16_f32 v83, v60, v64
	v_lshl_add_u64 v[34:35], v[86:87], 0, v[34:35]
	v_lshlrev_b64 v[38:39], 13, v[38:39]
	global_store_dwordx4 v[34:35], v[80:83], off nt
	v_cvt_pk_bf16_f32 v34, v37, v41
	v_cvt_pk_bf16_f32 v35, v45, v49
	v_cvt_pk_bf16_f32 v36, v53, v57
	v_cvt_pk_bf16_f32 v37, v61, v65
	v_lshl_add_u64 v[38:39], v[86:87], 0, v[38:39]
	global_store_dwordx4 v[38:39], v[34:37], off nt
	v_or_b32_e32 v38, 32, v84
	v_ashrrev_i32_e32 v39, 31, v38
	v_lshlrev_b64 v[38:39], 13, v[38:39]
	v_cvt_pk_bf16_f32 v34, v2, v6
	v_cvt_pk_bf16_f32 v35, v10, v14
	v_cvt_pk_bf16_f32 v36, v18, v22
	s_waitcnt vmcnt(4)
	v_cvt_pk_bf16_f32 v37, v26, v30
	v_lshl_add_u64 v[38:39], v[86:87], 0, v[38:39]
	v_or_b32_e32 v2, 33, v84
	global_store_dwordx4 v[38:39], v[34:37], off nt
	v_or_b32_e32 v6, 35, v84
	s_nop 0
	v_cvt_pk_bf16_f32 v34, v3, v7
	v_ashrrev_i32_e32 v3, 31, v2
	v_lshlrev_b64 v[2:3], 13, v[2:3]
	v_cvt_pk_bf16_f32 v35, v11, v15
	v_cvt_pk_bf16_f32 v36, v19, v23
	v_cvt_pk_bf16_f32 v37, v27, v31
	v_lshl_add_u64 v[2:3], v[86:87], 0, v[2:3]
	global_store_dwordx4 v[2:3], v[34:37], off nt
	v_or_b32_e32 v2, 34, v84
	v_ashrrev_i32_e32 v3, 31, v2
	v_lshlrev_b64 v[2:3], 13, v[2:3]
	v_ashrrev_i32_e32 v7, 31, v6
	v_cvt_pk_bf16_f32 v34, v4, v8
	v_cvt_pk_bf16_f32 v35, v12, v16
	v_cvt_pk_bf16_f32 v36, v20, v24
	v_cvt_pk_bf16_f32 v37, v28, v32
	v_lshl_add_u64 v[2:3], v[86:87], 0, v[2:3]
	v_lshlrev_b64 v[6:7], 13, v[6:7]
	global_store_dwordx4 v[2:3], v[34:37], off nt
	v_cvt_pk_bf16_f32 v2, v5, v9
	v_cvt_pk_bf16_f32 v3, v13, v17
	v_cvt_pk_bf16_f32 v4, v21, v25
	v_cvt_pk_bf16_f32 v5, v29, v33
	v_lshl_add_u64 v[6:7], v[86:87], 0, v[6:7]

.LBB0_114:
	s_and_b64 vcc, exec, s[22:23]
	s_cbranch_vccz .LBB0_116
	s_lshl_b64 s[22:23], s[14:15], 12
	s_add_u32 s15, s22, 0xf0900000
	s_addc_u32 s22, s23, 0xfff
	s_and_b32 s23, s22, 0xfff
	s_and_b32 s22, s15, 0xfff00000
	s_lshl_b64 s[24:25], s[22:23], 2
	v_readlane_b32 s52, v240, 2
	v_readlane_b32 s53, v240, 3
	s_add_u32 s15, s52, s24
	s_addc_u32 s24, s53, s25
	s_lshl_b64 s[22:23], s[22:23], 1
	s_add_u32 s25, s33, s22
	s_addc_u32 s26, s34, s23
	s_lshl_b32 s22, s14, 2
	s_and_b32 s27, s22, 0x3c0
	s_lshl_b32 s22, s14, 6
	s_and_b32 s28, s22, 0x3c0
	s_lshl_b32 s22, s28, 2
	s_add_u32 s22, s15, s22
	v_or_b32_e32 v1, s27, v66
	s_addc_u32 s23, s24, 0
	v_lshl_add_u64 v[34:35], s[22:23], 0, v[70:71]
	v_lshlrev_b32_e32 v30, 12, v1
	v_mov_b32_e32 v31, v71
	v_lshl_add_u64 v[36:37], v[34:35], 0, v[30:31]
	v_or_b32_e32 v38, 0x1000, v30
	v_mov_b32_e32 v39, v71
	v_or_b32_e32 v42, 0x2000, v30
	v_mov_b32_e32 v43, v71
	global_load_dwordx4 v[2:5], v[36:37], off nt
	v_lshl_add_u64 v[6:7], v[34:35], 0, v[38:39]
	v_lshl_add_u64 v[10:11], v[34:35], 0, v[42:43]
	v_or_b32_e32 v44, 0x3000, v30
	v_mov_b32_e32 v45, v71
	v_or_b32_e32 v50, 0x4000, v30
	v_mov_b32_e32 v51, v71
	v_or_b32_e32 v52, 0x5000, v30
	v_mov_b32_e32 v53, v71
	v_or_b32_e32 v58, 0x6000, v30
	v_mov_b32_e32 v59, v71
	v_or_b32_e32 v60, 0x7000, v30
	v_mov_b32_e32 v61, v71
	global_load_dwordx4 v[6:9], v[6:7], off nt
	s_nop 0
	global_load_dwordx4 v[10:13], v[10:11], off nt
	v_lshl_add_u64 v[14:15], v[34:35], 0, v[44:45]
	v_lshl_add_u64 v[18:19], v[34:35], 0, v[50:51]
	v_lshl_add_u64 v[22:23], v[34:35], 0, v[52:53]
	v_lshl_add_u64 v[26:27], v[34:35], 0, v[58:59]
	v_lshl_add_u64 v[30:31], v[34:35], 0, v[60:61]
	v_lshl_add_u64 v[62:63], v[34:35], 0, s[6:7]
	global_load_dwordx4 v[14:17], v[14:15], off nt
	s_nop 0
	global_load_dwordx4 v[18:21], v[18:19], off nt
	s_nop 0
	global_load_dwordx4 v[22:25], v[22:23], off nt
	s_nop 0
	global_load_dwordx4 v[26:29], v[26:27], off nt
	v_lshl_add_u64 v[38:39], v[62:63], 0, v[38:39]
	global_load_dwordx4 v[30:33], v[30:31], off nt
	v_lshl_add_u64 v[42:43], v[62:63], 0, v[42:43]
	v_lshl_add_u64 v[46:47], v[62:63], 0, v[44:45]
	v_lshl_add_u64 v[50:51], v[62:63], 0, v[50:51]
	v_lshl_add_u64 v[54:55], v[62:63], 0, v[52:53]
	v_lshl_add_u64 v[58:59], v[62:63], 0, v[58:59]
	v_lshl_add_u64 v[62:63], v[62:63], 0, v[60:61]
	global_load_dwordx4 v[34:37], v[36:37], off offset:128 nt
	s_lshl_b32 s15, s27, 1
	global_load_dwordx4 v[38:41], v[38:39], off nt
	s_nop 0
	global_load_dwordx4 v[42:45], v[42:43], off nt
	s_nop 0
	global_load_dwordx4 v[46:49], v[46:47], off nt
	s_nop 0
	global_load_dwordx4 v[50:53], v[50:51], off nt
	s_nop 0
	global_load_dwordx4 v[54:57], v[54:55], off nt
	s_nop 0
	global_load_dwordx4 v[58:61], v[58:59], off nt
	s_nop 0
	global_load_dwordx4 v[62:65], v[62:63], off nt
	s_add_u32 s22, s25, s15
	v_mov_b32_e32 v79, v71
	v_or_b32_e32 v1, s28, v68
	s_addc_u32 s23, s26, 0
	v_mov_b32_e32 v81, v71
	v_lshlrev_b32_e32 v80, 11, v1
	v_lshl_add_u64 v[82:83], s[22:23], 0, v[78:79]
	v_lshl_add_u64 v[92:93], v[82:83], 0, v[80:81]
	v_add_co_u32_e32 v94, vcc, s44, v92
	v_readlane_b32 s54, v240, 4
	s_nop 0
	v_addc_co_u32_e32 v95, vcc, 0, v93, vcc
	v_readlane_b32 s55, v240, 5
	v_readlane_b32 s56, v240, 6
	v_readlane_b32 s57, v240, 7
	v_readlane_b32 s58, v240, 8
	v_readlane_b32 s59, v240, 9
	s_waitcnt vmcnt(14)
	v_cvt_pk_bf16_f32 v80, v2, v6
	v_add_co_u32_e32 v6, vcc, s39, v92
	v_cvt_pk_bf16_f32 v84, v3, v7
	s_nop 0
	v_addc_co_u32_e32 v7, vcc, 0, v93, vcc
	v_cvt_pk_bf16_f32 v88, v4, v8
	s_waitcnt vmcnt(12)
	v_cvt_pk_bf16_f32 v81, v10, v14
	s_waitcnt vmcnt(10)
	v_cvt_pk_bf16_f32 v82, v18, v22
	v_cvt_pk_bf16_f32 v2, v5, v9
	v_cvt_pk_bf16_f32 v3, v13, v17
	s_waitcnt vmcnt(8)
	v_cvt_pk_bf16_f32 v83, v26, v30
	v_cvt_pk_bf16_f32 v4, v21, v25
	v_cvt_pk_bf16_f32 v5, v29, v33
	v_add_co_u32_e32 v8, vcc, s45, v92
	v_cvt_pk_bf16_f32 v85, v11, v15
	v_cvt_pk_bf16_f32 v86, v19, v23
	v_cvt_pk_bf16_f32 v87, v27, v31
	v_cvt_pk_bf16_f32 v89, v12, v16
	v_cvt_pk_bf16_f32 v90, v20, v24
	v_cvt_pk_bf16_f32 v91, v28, v32
	global_store_dwordx4 v[92:93], v[80:83], off nt
	global_store_dwordx4 v[92:93], v[84:87], off offset:2048 nt
	global_store_dwordx4 v[94:95], v[88:91], off nt
	global_store_dwordx4 v[94:95], v[2:5], off offset:2048 nt
	v_addc_co_u32_e32 v9, vcc, 0, v93, vcc
	s_waitcnt vmcnt(10)
	v_cvt_pk_bf16_f32 v2, v34, v38
	s_waitcnt vmcnt(8)
	v_cvt_pk_bf16_f32 v3, v42, v46
	s_waitcnt vmcnt(6)
	v_cvt_pk_bf16_f32 v4, v50, v54
	s_waitcnt vmcnt(4)
	v_cvt_pk_bf16_f32 v5, v58, v62
	global_store_dwordx4 v[8:9], v[2:5], off offset:-4096 nt
	s_nop 1
	v_cvt_pk_bf16_f32 v2, v35, v39
	v_cvt_pk_bf16_f32 v3, v43, v47
	v_cvt_pk_bf16_f32 v4, v51, v55
	v_cvt_pk_bf16_f32 v5, v59, v63
	global_store_dwordx4 v[6:7], v[2:5], off offset:2048 nt
	v_lshl_add_u64 v[6:7], v[92:93], 0, s[12:13]
	s_nop 0
	v_cvt_pk_bf16_f32 v2, v36, v40
	v_cvt_pk_bf16_f32 v3, v44, v48
	v_cvt_pk_bf16_f32 v4, v52, v56
	v_cvt_pk_bf16_f32 v5, v60, v64
	global_store_dwordx4 v[8:9], v[2:5], off nt
	s_nop 1
	v_cvt_pk_bf16_f32 v2, v37, v41
	v_cvt_pk_bf16_f32 v3, v45, v49
	v_cvt_pk_bf16_f32 v4, v53, v57
	v_cvt_pk_bf16_f32 v5, v61, v65

.LBB0_117:
	s_andn2_b64 vcc, exec, s[22:23]
	s_cbranch_vccnz .LBB0_90
	s_ashr_i32 s15, s14, 31
	s_lshr_b32 s15, s15, 25
	s_add_i32 s15, s14, s15
	s_ashr_i32 s22, s15, 7
	s_and_b32 s15, s15, 0xffffff80
	s_sub_i32 s15, s14, s15
	s_lshl_b32 s14, s22, 6
	s_lshl_b32 s22, s15, 6
	v_or_b32_e32 v30, s14, v66
	s_cmp_lt_i32 s15, 64
	v_or_b32_e32 v6, 1, v30
	s_cselect_b32 s24, 0, 0xfffff000
	s_cselect_b32 s25, 0, 0x80
	s_ashr_i32 s23, s22, 31
	v_ashrrev_i32_e32 v31, 31, v30
	v_ashrrev_i32_e32 v7, 31, v6
	v_lshl_add_u64 v[32:33], s[22:23], 2, v[72:73]
	v_lshlrev_b64 v[2:3], 15, v[30:31]
	v_lshlrev_b64 v[6:7], 15, v[6:7]
	v_or_b32_e32 v10, 2, v30
	v_or_b32_e32 v14, 3, v30
	v_or_b32_e32 v18, 4, v30
	v_or_b32_e32 v22, 5, v30
	v_or_b32_e32 v26, 6, v30
	v_lshl_add_u64 v[34:35], v[32:33], 0, v[2:3]
	v_lshl_add_u64 v[38:39], v[32:33], 0, v[6:7]
	v_ashrrev_i32_e32 v11, 31, v10
	v_ashrrev_i32_e32 v15, 31, v14
	v_ashrrev_i32_e32 v19, 31, v18
	v_ashrrev_i32_e32 v23, 31, v22
	v_ashrrev_i32_e32 v27, 31, v26
	global_load_dwordx4 v[2:5], v[34:35], off nt
	global_load_dwordx4 v[6:9], v[38:39], off nt
	v_lshlrev_b64 v[10:11], 15, v[10:11]
	v_lshlrev_b64 v[14:15], 15, v[14:15]
	v_lshlrev_b64 v[18:19], 15, v[18:19]
	v_lshlrev_b64 v[22:23], 15, v[22:23]
	v_lshlrev_b64 v[26:27], 15, v[26:27]
	v_lshl_add_u64 v[42:43], v[32:33], 0, v[10:11]
	v_lshl_add_u64 v[46:47], v[32:33], 0, v[14:15]
	v_lshl_add_u64 v[50:51], v[32:33], 0, v[18:19]
	v_lshl_add_u64 v[54:55], v[32:33], 0, v[22:23]
	v_lshl_add_u64 v[58:59], v[32:33], 0, v[26:27]
	global_load_dwordx4 v[10:13], v[42:43], off nt
	global_load_dwordx4 v[14:17], v[46:47], off nt
	global_load_dwordx4 v[18:21], v[50:51], off nt
	global_load_dwordx4 v[22:25], v[54:55], off nt
	global_load_dwordx4 v[26:29], v[58:59], off nt
	v_or_b32_e32 v30, 7, v30
	v_ashrrev_i32_e32 v31, 31, v30
	v_lshlrev_b64 v[30:31], 15, v[30:31]
	v_lshl_add_u64 v[62:63], v[32:33], 0, v[30:31]
	global_load_dwordx4 v[30:33], v[62:63], off nt
	s_nop 0
	global_load_dwordx4 v[34:37], v[34:35], off offset:128 nt
	s_nop 0
	global_load_dwordx4 v[38:41], v[38:39], off offset:128 nt
	s_nop 0
	global_load_dwordx4 v[42:45], v[42:43], off offset:128 nt
	s_nop 0
	global_load_dwordx4 v[46:49], v[46:47], off offset:128 nt
	s_nop 0
	global_load_dwordx4 v[50:53], v[50:51], off offset:128 nt
	s_nop 0
	global_load_dwordx4 v[54:57], v[54:55], off offset:128 nt
	s_nop 0
	global_load_dwordx4 v[58:61], v[58:59], off offset:128 nt
	s_nop 0
	global_load_dwordx4 v[62:65], v[62:63], off offset:128 nt
	s_ashr_i32 s15, s14, 31
	s_add_i32 s24, s24, s22
	s_and_b32 s23, s22, 64
	v_lshl_add_u64 v[92:93], s[14:15], 1, v[74:75]
	s_lshl_b32 s14, s24, 1
	s_or_b32 s22, s25, s23
	s_and_b32 s14, s14, 0xffffff00
	s_or_b32 s14, s22, s14
	v_or_b32_e32 v94, s14, v68
	v_or_b32_e32 v80, 1, v94
	v_ashrrev_i32_e32 v81, 31, v80
	v_or_b32_e32 v96, 2, v94
	v_lshlrev_b64 v[80:81], 13, v[80:81]
	v_ashrrev_i32_e32 v95, 31, v94
	v_lshl_add_u64 v[100:101], v[92:93], 0, v[80:81]
	v_ashrrev_i32_e32 v97, 31, v96
	v_lshlrev_b64 v[82:83], 13, v[94:95]
	v_lshl_add_u64 v[98:99], v[92:93], 0, v[82:83]
	s_waitcnt vmcnt(14)
	v_cvt_pk_bf16_f32 v80, v2, v6
	v_or_b32_e32 v6, 3, v94
	v_cvt_pk_bf16_f32 v84, v3, v7
	v_lshlrev_b64 v[2:3], 13, v[96:97]
	v_ashrrev_i32_e32 v7, 31, v6
	v_cvt_pk_bf16_f32 v88, v4, v8
	v_lshl_add_u64 v[2:3], v[92:93], 0, v[2:3]
	v_lshlrev_b64 v[6:7], 13, v[6:7]
	v_lshl_add_u64 v[6:7], v[92:93], 0, v[6:7]
	s_waitcnt vmcnt(12)
	v_cvt_pk_bf16_f32 v81, v10, v14
	v_cvt_pk_bf16_f32 v89, v12, v16
	s_waitcnt vmcnt(10)
	v_cvt_pk_bf16_f32 v82, v18, v22
	s_waitcnt vmcnt(8)
	v_cvt_pk_bf16_f32 v83, v26, v30
	v_cvt_pk_bf16_f32 v90, v20, v24
	v_cvt_pk_bf16_f32 v91, v28, v32
	v_cvt_pk_bf16_f32 v85, v11, v15
	v_cvt_pk_bf16_f32 v86, v19, v23
	v_cvt_pk_bf16_f32 v87, v27, v31
	global_store_dwordx4 v[98:99], v[80:83], off nt
	global_store_dwordx4 v[100:101], v[84:87], off nt
	global_store_dwordx4 v[2:3], v[88:91], off nt
	v_cvt_pk_bf16_f32 v2, v5, v9
	v_cvt_pk_bf16_f32 v3, v13, v17
	v_cvt_pk_bf16_f32 v4, v21, v25
	v_cvt_pk_bf16_f32 v5, v29, v33
	global_store_dwordx4 v[6:7], v[2:5], off nt
	v_or_b32_e32 v6, 32, v94
	v_ashrrev_i32_e32 v7, 31, v6
	v_lshlrev_b64 v[6:7], 13, v[6:7]
	s_waitcnt vmcnt(10)
	v_cvt_pk_bf16_f32 v2, v34, v38
	s_waitcnt vmcnt(8)
	v_cvt_pk_bf16_f32 v3, v42, v46
	s_waitcnt vmcnt(6)
	v_cvt_pk_bf16_f32 v4, v50, v54
	s_waitcnt vmcnt(4)
	v_cvt_pk_bf16_f32 v5, v58, v62
	v_lshl_add_u64 v[6:7], v[92:93], 0, v[6:7]
	global_store_dwordx4 v[6:7], v[2:5], off nt
	v_or_b32_e32 v6, 33, v94
	v_ashrrev_i32_e32 v7, 31, v6
	v_lshlrev_b64 v[6:7], 13, v[6:7]
	v_cvt_pk_bf16_f32 v2, v35, v39
	v_cvt_pk_bf16_f32 v3, v43, v47
	v_cvt_pk_bf16_f32 v4, v51, v55
	v_cvt_pk_bf16_f32 v5, v59, v63
	v_lshl_add_u64 v[6:7], v[92:93], 0, v[6:7]
	global_store_dwordx4 v[6:7], v[2:5], off nt
	v_or_b32_e32 v6, 34, v94
	v_ashrrev_i32_e32 v7, 31, v6
	v_lshlrev_b64 v[6:7], 13, v[6:7]
	v_cvt_pk_bf16_f32 v2, v36, v40
	v_cvt_pk_bf16_f32 v3, v44, v48
	v_cvt_pk_bf16_f32 v4, v52, v56
	v_cvt_pk_bf16_f32 v5, v60, v64
	v_lshl_add_u64 v[6:7], v[92:93], 0, v[6:7]
	global_store_dwordx4 v[6:7], v[2:5], off nt
	v_or_b32_e32 v6, 35, v94
	v_ashrrev_i32_e32 v7, 31, v6
	v_lshlrev_b64 v[6:7], 13, v[6:7]
	v_cvt_pk_bf16_f32 v2, v37, v41
	v_cvt_pk_bf16_f32 v3, v45, v49
	v_cvt_pk_bf16_f32 v4, v53, v57
	v_cvt_pk_bf16_f32 v5, v61, v65
	v_lshl_add_u64 v[6:7], v[92:93], 0, v[6:7]
	s_branch .LBB0_90
